# adds all four retention heads' K/V chunk loads issued up front before the head loop (no in-loop prefetch), counted waits
# speedup vs baseline: 1.0066x; 1.0066x over previous
; DI void kv_chunk(CP p, int b, int n, LAS unsigned char* lds) {
;     ...
;     {
;         u32x4 rv0, rv1, rk0, rk1;
;     ...
;         KVR_LOAD(0);
.LBB0_296:
	v_mov_b32_e32 v33, v199
	s_waitcnt vmcnt(0)
	s_barrier
	s_waitcnt vmcnt(0)
	buffer_inv sc1
	s_add_u32 s52, s50, 0x2000
	v_ashrrev_i32_e32 v38, 6, v33
	v_ashrrev_i32_e32 v22, 4, v33
	v_and_b32_e32 v32, 63, v33
	v_add_u32_e32 v18, 32, v22
	v_lshlrev_b32_e32 v16, 3, v38
	v_ashrrev_i32_e32 v23, 31, v22
	v_ashrrev_i32_e32 v19, 31, v18
	v_lshlrev_b32_e32 v24, 14, v32
	v_mov_b32_e32 v25, v197
	v_ashrrev_i32_e32 v17, 31, v16
	s_addc_u32 s53, s51, 0
	v_lshlrev_b64 v[26:27], 14, v[22:23]
	v_lshlrev_b64 v[2:3], 14, v[18:19]
	v_lshl_add_u64 v[8:9], s[50:51], 0, v[24:25]
	v_lshlrev_b64 v[36:37], 1, v[16:17]
	v_and_b32_e32 v44, 15, v33
	v_lshl_add_u64 v[0:1], s[52:53], 0, v[26:27]
	v_lshl_add_u64 v[2:3], s[52:53], 0, v[2:3]
	v_lshl_add_u64 v[8:9], v[8:9], 0, v[36:37]
	s_mov_b64 s[52:53], 0x1c00
	s_movk_i32 s22, 0x1000
	v_lshlrev_b32_e32 v196, 4, v44
	v_lshl_add_u64 v[12:13], v[8:9], 0, s[52:53]
	v_add_co_u32_e32 v8, vcc, s22, v8
	v_lshl_add_u64 v[0:1], v[0:1], 0, v[196:197]
	v_lshl_add_u64 v[4:5], v[2:3], 0, v[196:197]
	v_addc_co_u32_e32 v9, vcc, 0, v9, vcc
	global_load_dwordx4 v[0:3], v[0:1], off
	s_nop 0
	global_load_dwordx4 v[4:7], v[4:5], off
	s_nop 0
	global_load_dwordx4 v[8:11], v[8:9], off offset:3072
	s_nop 0
	global_load_dwordx4 v[12:15], v[12:13], off offset:128
	v_readfirstlane_b32 s22, v38
	s_movk_i32 s52, 0x110
	s_lshl_b32 s60, s22, 4
	v_lshlrev_b64 v[28:29], 13, v[22:23]
	v_mul_lo_u32 v21, v22, s52
	v_or_b32_e32 v22, s60, v44
	s_movk_i32 s52, 0x90
	v_bfe_u32 v34, v33, 4, 2
	v_mul_lo_u32 v22, v22, s52
	v_add_u32_e32 v41, 0, v22
	v_lshlrev_b32_e32 v22, 3, v34
	v_bfe_u32 v23, v33, 2, 2
	s_ashr_i32 s61, s60, 31
	s_lshl_b32 s56, s56, 7
	v_or_b32_e32 v39, v22, v23
	v_lshlrev_b32_e32 v23, 3, v33
	s_lshl_b64 s[52:53], s[60:61], 1
	v_readlane_b32 s61, v254, 61
	v_and_b32_e32 v23, 24, v23
	s_add_u32 s52, s61, s52
	v_readlane_b32 s61, v254, 62
	v_add_u32_e32 v35, 0, v23
	s_addc_u32 s53, s61, s53
	v_mov_b32_e32 v23, v197
	v_lshl_add_u64 v[22:23], s[52:53], 0, v[22:23]
	s_movk_i32 s52, 0x480
	v_lshlrev_b64 v[30:31], 13, v[18:19]
	v_bitop3_b32 v19, v33, 63, v33 bitop3:0xc
	v_and_b32_e32 v47, 48, v33
	v_mul_lo_u32 v33, v38, s52
	s_lshl_b64 s[52:53], s[64:65], 14
	v_lshl_add_u64 v[24:25], s[52:53], 0, v[24:25]
	v_lshl_add_u64 v[26:27], v[26:27], 0, s[52:53]
	s_or_b32 s64, s56, s84
	v_readlane_b32 s84, v253, 47
	v_add_u32_e32 v40, 0, v21
	v_lshl_add_u32 v21, v32, 1, 0
	v_add_u32_e32 v42, 0x2400, v33
	v_mul_u32_u24_e32 v50, 0x110, v39
	v_lshlrev_b32_e32 v38, 8, v44
	v_mov_b32_e32 v39, v197
	v_lshl_add_u64 v[24:25], v[24:25], 0, v[36:37]
	v_or_b32_e32 v26, v26, v196
	v_readlane_b32 s85, v253, 48
	v_lshlrev_b32_e32 v20, 3, v44
	v_lshlrev_b32_e32 v18, 13, v32
	s_mov_b32 s57, 0
	v_cvt_f32_ubyte0_e32 v19, v19
	v_lshlrev_b32_e32 v34, 2, v34
	v_lshl_add_u64 v[22:23], v[22:23], 0, v[38:39]
	v_lshl_add_u64 v[24:25], s[12:13], 0, v[24:25]
	v_lshl_add_u64 v[26:27], s[12:13], 0, v[26:27]
	s_mov_b64 s[72:73], 0
	v_add_u32_e32 v36, v21, v42
	v_add_u32_e32 v37, v41, v47
	v_add_u32_e32 v48, v40, v196
	v_readlane_b32 s85, v253, 54
	v_and_b32_e32 v67, 15, v199
	v_mul_u32_u24_e32 v64, 0x110, v67
	v_bfe_u32 v67, v199, 4, 2
	v_lshl_add_u32 v64, v67, 3, v64
	v_lshrrev_b32_e32 v67, 6, v199
	v_lshl_add_u32 v64, v67, 5, v64
	v_add_u32_e32 v64, 0xa000, v64
	v_lshrrev_b32_e32 v67, 4, v199
	v_mul_u32_u24_e32 v65, 0x110, v67
	v_and_b32_e32 v67, 15, v199
	v_lshl_add_u32 v65, v67, 4, v65
	v_add_u32_e32 v65, 0xa000, v65
	v_lshlrev_b32_e32 v66, 4, v199
	v_mov_b32_e32 v67, 0
	v_readlane_b32 s100, v254, 61
	v_readlane_b32 s101, v254, 62
	s_nop 1
	v_lshl_add_u64 v[68:69], s[100:101], 0, v[66:67]
	s_mov_b32 s100, 0x0
	s_mov_b32 s101, 0
	v_lshl_add_u64 v[70:71], v[26:27], 0, s[100:101]
	v_lshl_add_u64 v[76:77], v[24:25], 0, s[100:101]
	v_add_co_u32_e32 v72, vcc, 0xba02000, v70
	s_nop 1
	v_addc_co_u32_e32 v73, vcc, 0, v71, vcc
	v_add_co_u32_e32 v74, vcc, 0xba82000, v70
	s_nop 1
	v_addc_co_u32_e32 v75, vcc, 0, v71, vcc
	v_add_co_u32_e32 v78, vcc, 0xba01000, v76
	s_nop 1
	v_addc_co_u32_e32 v79, vcc, 0, v77, vcc
	global_load_dwordx4 v[94:97], v[72:73], off offset:256
	global_load_dwordx4 v[98:101], v[74:75], off offset:256
	global_load_dwordx4 v[102:105], v[78:79], off offset:3328
	global_load_dwordx4 v[106:109], v[78:79], off offset:3456
	s_mov_b32 s100, 0x100
	s_mov_b32 s101, 0
	v_lshl_add_u64 v[70:71], v[26:27], 0, s[100:101]
	v_lshl_add_u64 v[76:77], v[24:25], 0, s[100:101]
	v_add_co_u32_e32 v72, vcc, 0xba02000, v70
	s_nop 1
	v_addc_co_u32_e32 v73, vcc, 0, v71, vcc
	v_add_co_u32_e32 v74, vcc, 0xba82000, v70
	s_nop 1
	v_addc_co_u32_e32 v75, vcc, 0, v71, vcc
	v_add_co_u32_e32 v78, vcc, 0xba01000, v76
	s_nop 1
	v_addc_co_u32_e32 v79, vcc, 0, v77, vcc
	global_load_dwordx4 v[110:113], v[72:73], off offset:256
	global_load_dwordx4 v[114:117], v[74:75], off offset:256
	global_load_dwordx4 v[118:121], v[78:79], off offset:3328
	global_load_dwordx4 v[122:125], v[78:79], off offset:3456
	s_mov_b32 s100, 0x200
	s_mov_b32 s101, 0
	v_lshl_add_u64 v[70:71], v[26:27], 0, s[100:101]
	v_lshl_add_u64 v[76:77], v[24:25], 0, s[100:101]
	v_add_co_u32_e32 v72, vcc, 0xba02000, v70
	s_nop 1
	v_addc_co_u32_e32 v73, vcc, 0, v71, vcc
	v_add_co_u32_e32 v74, vcc, 0xba82000, v70
	s_nop 1
	v_addc_co_u32_e32 v75, vcc, 0, v71, vcc
	v_add_co_u32_e32 v78, vcc, 0xba01000, v76
	s_nop 1
	v_addc_co_u32_e32 v79, vcc, 0, v77, vcc
	global_load_dwordx4 v[126:129], v[72:73], off offset:256
	global_load_dwordx4 v[130:133], v[74:75], off offset:256
	global_load_dwordx4 v[134:137], v[78:79], off offset:3328
	global_load_dwordx4 v[138:141], v[78:79], off offset:3456
	s_branch .LBB0_298

; #define LAS __attribute__((address_space(3)))
; DI unsigned pk2(float lo, float hi) { f32x2_t v = {lo, hi}; bf16x2_t b = __builtin_convertvector(v, bf16x2_t); return __builtin_bit_cast(unsigned, b); }
; DI void unpack8(const u32x4 w, float (&f)[8]) { f[0] = bflo(w.x); f[1] = bfhi(w.x); f[2] = bflo(w.y); f[3] = bfhi(w.y); f[4] = bflo(w.z); f[5] = bfhi(w.z); f[6] = bflo(w.w); f[7] = bfhi(w.w); }
; DI float fexp2(float x) { return __builtin_amdgcn_exp2f(x); }
; DI void kv_chunk(CP p, int b, int n, LAS unsigned char* lds) {
;     ...
;         for (int h = 0; h < 4; ++h) {
;             const float w = fexp2((float)(63 - kj) * log2gamma(h));
;             *(LAS u32x4*)(lds + VT + (tid >> 4) * 272 + (tid & 15) * 16) = rv0; *(LAS u32x4*)(lds + VT + (32 + (tid >> 4)) * 272 + (tid & 15) * 16) = rv1;
;             { float x[8]; unpack8(rk0, x);
; #pragma unroll
;               for (int e = 0; e < 8; ++e) *(LAS bf16*)(lds + KT + (kpt * 8 + e) * 144 + kj * 2) = (bf16)(pk2(x[e] * w, 0.f) & 0xffffu);
;               unpack8(rk1, x);
; #pragma unroll
;               for (int e = 0; e < 8; ++e) *(LAS bf16*)(lds + KT + ((kpt + 8) * 8 + e) * 144 + kj * 2) = (bf16)(pk2(x[e] * w, 0.f) & 0xffffu); }
;             if (h < 3) KVR_LOAD(h + 1);
;             __syncthreads();
.LBB0_303:
	v_mul_f32_e32 v38, v38, v19
	v_exp_f32_e32 v38, v38
	s_cmp_lt_i32 s57, 1
	s_cbranch_scc1 .Lkvp_h0
	s_waitcnt vmcnt(8)
	s_cmp_eq_u32 s57, 1
	s_cbranch_scc1 .Lkvp_c1
	s_cmp_eq_u32 s57, 2
	s_cbranch_scc1 .Lkvp_c2
	v_mov_b32_e32 v0, v126
	v_mov_b32_e32 v1, v127
	v_mov_b32_e32 v2, v128
	v_mov_b32_e32 v3, v129
	v_mov_b32_e32 v4, v130
	v_mov_b32_e32 v5, v131
	v_mov_b32_e32 v6, v132
	v_mov_b32_e32 v7, v133
	v_mov_b32_e32 v8, v134
	v_mov_b32_e32 v9, v135
	v_mov_b32_e32 v10, v136
	v_mov_b32_e32 v11, v137
	v_mov_b32_e32 v12, v138
	v_mov_b32_e32 v13, v139
	v_mov_b32_e32 v14, v140
	v_mov_b32_e32 v15, v141
	s_branch .Lkvp_go
.Lkvp_c2:
	v_mov_b32_e32 v0, v110
	v_mov_b32_e32 v1, v111
	v_mov_b32_e32 v2, v112
	v_mov_b32_e32 v3, v113
	v_mov_b32_e32 v4, v114
	v_mov_b32_e32 v5, v115
	v_mov_b32_e32 v6, v116
	v_mov_b32_e32 v7, v117
	v_mov_b32_e32 v8, v118
	v_mov_b32_e32 v9, v119
	v_mov_b32_e32 v10, v120
	v_mov_b32_e32 v11, v121
	v_mov_b32_e32 v12, v122
	v_mov_b32_e32 v13, v123
	v_mov_b32_e32 v14, v124
	v_mov_b32_e32 v15, v125
	s_branch .Lkvp_go
.Lkvp_c1:
	v_mov_b32_e32 v0, v94
	v_mov_b32_e32 v1, v95
	v_mov_b32_e32 v2, v96
	v_mov_b32_e32 v3, v97
	v_mov_b32_e32 v4, v98
	v_mov_b32_e32 v5, v99
	v_mov_b32_e32 v6, v100
	v_mov_b32_e32 v7, v101
	v_mov_b32_e32 v8, v102
	v_mov_b32_e32 v9, v103
	v_mov_b32_e32 v10, v104
	v_mov_b32_e32 v11, v105
	v_mov_b32_e32 v12, v106
	v_mov_b32_e32 v13, v107
	v_mov_b32_e32 v14, v108
	v_mov_b32_e32 v15, v109
	s_branch .Lkvp_go
.Lkvp_h0:
	s_waitcnt vmcnt(13)
.Lkvp_go:
	v_lshlrev_b32_e32 v39, 16, v8
	v_and_b32_e32 v40, 0xffff0000, v8
	v_add_u32_e32 v49, v21, v33
	v_mul_f32_e32 v39, v38, v39
	v_cvt_pk_bf16_f32 v39, v39, s0
	ds_write_b128 v48, v[0:3]
	ds_write_b128 v48, v[4:7] offset:8704
	ds_write_b16 v49, v39 offset:18432
	v_mul_f32_e32 v39, v38, v40
	v_lshlrev_b32_e32 v41, 16, v9
	v_cvt_pk_bf16_f32 v39, v39, s0
	ds_write_b16 v49, v39 offset:18576
	v_mul_f32_e32 v39, v38, v41
	v_and_b32_e32 v42, 0xffff0000, v9
	v_cvt_pk_bf16_f32 v39, v39, s0
	ds_write_b16 v49, v39 offset:18720
	v_mul_f32_e32 v39, v38, v42
	v_lshlrev_b32_e32 v43, 16, v10
	v_cvt_pk_bf16_f32 v39, v39, s0
	ds_write_b16 v49, v39 offset:18864
	v_mul_f32_e32 v39, v38, v43
	v_and_b32_e32 v45, 0xffff0000, v10
	v_cvt_pk_bf16_f32 v39, v39, s0
	ds_write_b16 v49, v39 offset:19008
	v_mul_f32_e32 v39, v38, v45
	v_lshlrev_b32_e32 v46, 16, v11
	v_cvt_pk_bf16_f32 v39, v39, s0
	ds_write_b16 v49, v39 offset:19152
	v_mul_f32_e32 v39, v38, v46
	v_and_b32_e32 v51, 0xffff0000, v11
	v_cvt_pk_bf16_f32 v39, v39, s0
	ds_write_b16 v49, v39 offset:19296
	v_mul_f32_e32 v39, v38, v51
	v_cvt_pk_bf16_f32 v39, v39, s0
	ds_write_b16 v49, v39 offset:19440
	s_waitcnt vmcnt(12)
	s_cmp_lt_i32 s57, 1
	s_cbranch_scc1 .Lkvl_skip
	s_add_i32 s100, s64, -32
	s_mov_b32 s101, 0
	s_lshl_b64 s[100:101], s[100:101], 15
	v_lshl_add_u64 v[70:71], v[68:69], 0, s[100:101]
	s_mov_b64 s[100:101], 0x2000
	v_lshl_add_u64 v[88:89], v[70:71], 0, s[100:101]
	v_lshl_add_u64 v[90:91], v[88:89], 0, s[100:101]
	v_lshl_add_u64 v[92:93], v[90:91], 0, s[100:101]
	ds_read_b128 v[72:75], v65
	ds_read_b128 v[76:79], v65 offset:8704
	ds_read_b128 v[80:83], v65 offset:17408
	ds_read_b128 v[84:87], v65 offset:26112
	s_waitcnt lgkmcnt(3)
	global_store_dwordx4 v[70:71], v[72:75], off
	s_waitcnt lgkmcnt(2)
	global_store_dwordx4 v[88:89], v[76:79], off
	s_waitcnt lgkmcnt(1)
	global_store_dwordx4 v[90:91], v[80:83], off
	s_waitcnt lgkmcnt(0)
	global_store_dwordx4 v[92:93], v[84:87], off
.Lkvl_skip:
	v_lshlrev_b32_e32 v39, 16, v12
	v_mul_f32_e32 v39, v38, v39
	v_and_b32_e32 v40, 0xffff0000, v12
	v_cvt_pk_bf16_f32 v39, v39, s0
	ds_write_b16 v36, v39 offset:18432
	v_mul_f32_e32 v39, v38, v40
	v_lshlrev_b32_e32 v41, 16, v13
	v_cvt_pk_bf16_f32 v39, v39, s0
	ds_write_b16 v49, v39 offset:27792
	v_mul_f32_e32 v39, v38, v41
	v_and_b32_e32 v42, 0xffff0000, v13
	v_cvt_pk_bf16_f32 v39, v39, s0
	ds_write_b16 v49, v39 offset:27936
	v_mul_f32_e32 v39, v38, v42
	v_lshlrev_b32_e32 v43, 16, v14
	v_cvt_pk_bf16_f32 v39, v39, s0
	ds_write_b16 v49, v39 offset:28080
	v_mul_f32_e32 v39, v38, v43
	v_and_b32_e32 v45, 0xffff0000, v14
	v_cvt_pk_bf16_f32 v39, v39, s0
	ds_write_b16 v49, v39 offset:28224
	v_mul_f32_e32 v39, v38, v45
	v_lshlrev_b32_e32 v46, 16, v15
	v_and_b32_e32 v51, 0xffff0000, v15
	v_cvt_pk_bf16_f32 v39, v39, s0
	ds_write_b16 v49, v39 offset:28368
	v_mul_f32_e32 v39, v38, v46
	v_mul_f32_e32 v38, v38, v51
	v_cvt_pk_bf16_f32 v39, v39, s0
	v_cvt_pk_bf16_f32 v38, v38, s0
	s_cmpk_eq_i32 s72, 0x300
	ds_write_b16 v49, v39 offset:28512
	ds_write_b16 v49, v38 offset:28656
	s_cbranch_scc1 .LBB0_297
	v_lshl_add_u64 v[0:1], v[26:27], 0, s[72:73]
	v_add_co_u32_e32 v2, vcc, 0xba02000, v0
	v_lshl_add_u64 v[8:9], v[24:25], 0, s[72:73]
	s_nop 0
	v_addc_co_u32_e32 v3, vcc, 0, v1, vcc
	v_add_co_u32_e32 v4, vcc, 0xba82000, v0
	s_nop 1
	v_addc_co_u32_e32 v5, vcc, 0, v1, vcc
	v_add_co_u32_e32 v12, vcc, 0xba01000, v8
	s_nop 0
	v_addc_co_u32_e32 v13, vcc, 0, v9, vcc
	s_nop 0
	s_branch .LBB0_297
